# opt16
# speedup vs baseline: 1.0122x; 1.0122x over previous
; __device__ __forceinline__ float b2f(u16 b) { return __uint_as_float(((uint32_t)b) << 16); }
; template <int K, bool HG>
; __device__ void chunk_item(const Ctx& cx, CParamsPtr pp, int l, int item, char* shm) {
;     ...
;       const float qraw = b2f(rq[i]), kraw = b2f(rk[i]);
;       float gi;
;       if (HG) {
;         const float sg = 1.0f / (1.0f + __expf(-kraw));
;         const float f = fmaxf(lbv + (1.0f - lbv) * sg, 1e-12f);
;         gi = __logf(f);
;         kvv[i] = (1.0f - lbv) * (1.0f - sg);
;         qvv[i] = qraw / (1.0f + __expf(-qraw)) * 0.08838834764831845f;
.LBB0_192:
	s_waitcnt vmcnt(16)
	v_lshlrev_b32_e32 v1, 16, v83
	v_mul_f32_e32 v2, 0xbfb8aa3b, v1
	v_exp_f32_e32 v2, v2
	s_and_b32 s18, s31, 0x10000
	s_add_i32 s34, s18, 0
	s_waitcnt vmcnt(2)
	v_lshlrev_b32_e32 v64, 16, v64
	v_add_f32_e32 v2, 1.0, v2
	v_div_scale_f32 v49, s[18:19], v2, v2, v1
	v_rcp_f32_e32 v56, v49
	s_cmp_lg_u32 s22, 0xf80000
	v_lshlrev_b32_e32 v0, 16, v85
	v_mul_f32_e32 v0, 0xbfb8aa3b, v0
	v_fma_f32 v57, -v49, v56, 1.0
	v_fmac_f32_e32 v56, v57, v56
	v_div_scale_f32 v57, vcc, v1, v2, v1
	v_mul_f32_e32 v58, v57, v56
	v_fma_f32 v59, -v49, v58, v57
	v_fmac_f32_e32 v58, v59, v56
	v_fma_f32 v49, -v49, v58, v57
	v_div_fmas_f32 v49, v49, v56, v58
	v_div_fixup_f32 v1, v49, v2, v1
	v_lshlrev_b32_e32 v49, 16, v81
	v_mul_f32_e32 v56, 0xbfb8aa3b, v49
	v_exp_f32_e32 v56, v56
	v_mul_f32_e32 v2, 0x3db504f3, v1
	v_lshlrev_b32_e32 v1, 16, v82
	v_mul_f32_e32 v1, 0xbfb8aa3b, v1
	v_add_f32_e32 v56, 1.0, v56
	v_div_scale_f32 v57, s[18:19], v56, v56, v49
	v_rcp_f32_e32 v58, v57
	v_exp_f32_e32 v0, v0
	v_exp_f32_e32 v1, v1
	v_fma_f32 v59, -v57, v58, 1.0
	v_fmac_f32_e32 v58, v59, v58
	v_div_scale_f32 v59, vcc, v49, v56, v49
	v_mul_f32_e32 v60, v59, v58
	v_fma_f32 v61, -v57, v60, v59
	v_fmac_f32_e32 v60, v61, v58
	v_fma_f32 v57, -v57, v60, v59
	v_div_fmas_f32 v57, v57, v58, v60
	v_div_fixup_f32 v49, v57, v56, v49
	v_lshlrev_b32_e32 v57, 16, v78
	v_mul_f32_e32 v58, 0xbfb8aa3b, v57
	v_exp_f32_e32 v58, v58
	v_lshlrev_b32_e32 v56, 16, v79
	v_mul_f32_e32 v56, 0xbfb8aa3b, v56
	v_exp_f32_e32 v56, v56
	v_add_f32_e32 v58, 1.0, v58
	v_div_scale_f32 v59, s[18:19], v58, v58, v57
	v_rcp_f32_e32 v60, v59
	v_pk_add_f32 v[0:1], v[0:1], 1.0 op_sel_hi:[1,0]
	v_mul_f32_e32 v49, 0x3db504f3, v49
	v_fma_f32 v61, -v59, v60, 1.0
	v_fmac_f32_e32 v60, v61, v60
	v_div_scale_f32 v61, vcc, v57, v58, v57
	v_mul_f32_e32 v78, v61, v60
	v_fma_f32 v79, -v59, v78, v61
	v_fmac_f32_e32 v78, v79, v60
	v_fma_f32 v59, -v59, v78, v61
	v_div_fmas_f32 v59, v59, v60, v78
	v_div_fixup_f32 v57, v59, v58, v57
	v_lshlrev_b32_e32 v58, 16, v76
	v_mul_f32_e32 v59, 0xbfb8aa3b, v58
	v_exp_f32_e32 v59, v59
	v_mul_f32_e32 v92, 0x3db504f3, v57
	v_lshlrev_b32_e32 v57, 16, v77
	v_mul_f32_e32 v57, 0xbfb8aa3b, v57
	v_add_f32_e32 v59, 1.0, v59
	v_div_scale_f32 v60, s[18:19], v59, v59, v58
	v_rcp_f32_e32 v61, v60
	v_exp_f32_e32 v57, v57
	v_fma_f32 v76, -v60, v61, 1.0
	v_fmac_f32_e32 v61, v76, v61
	v_div_scale_f32 v76, vcc, v58, v59, v58
	v_mul_f32_e32 v77, v76, v61
	v_fma_f32 v78, -v60, v77, v76
	v_fmac_f32_e32 v77, v78, v61
	v_fma_f32 v60, -v60, v77, v76
	v_div_fmas_f32 v60, v60, v61, v77
	v_div_fixup_f32 v58, v60, v59, v58
	v_lshlrev_b32_e32 v59, 16, v74
	v_mul_f32_e32 v93, 0x3db504f3, v58
	v_lshlrev_b32_e32 v58, 16, v73
	v_mul_f32_e32 v59, 0xbfb8aa3b, v59
	v_exp_f32_e32 v60, v59
	v_mul_f32_e32 v59, 0xbfb8aa3b, v58
	v_exp_f32_e32 v59, v59
	v_pk_add_f32 v[56:57], v[56:57], 1.0 op_sel_hi:[1,0]
	v_add_f32_e32 v59, 1.0, v59
	v_div_scale_f32 v61, s[18:19], v59, v59, v58
	v_rcp_f32_e32 v73, v61
	s_nop 0
	v_fma_f32 v74, -v61, v73, 1.0
	v_fmac_f32_e32 v73, v74, v73
	v_div_scale_f32 v74, vcc, v58, v59, v58
	v_mul_f32_e32 v76, v74, v73
	v_fma_f32 v77, -v61, v76, v74
	v_fmac_f32_e32 v76, v77, v73
	v_fma_f32 v61, -v61, v76, v74
	v_div_fmas_f32 v61, v61, v73, v76
	v_div_fixup_f32 v58, v61, v59, v58
	v_lshlrev_b32_e32 v59, 16, v72
	v_mul_f32_e32 v94, 0x3db504f3, v58
	v_lshlrev_b32_e32 v58, 16, v71
	v_mul_f32_e32 v59, 0xbfb8aa3b, v59
	v_exp_f32_e32 v61, v59
	v_mul_f32_e32 v59, 0xbfb8aa3b, v58
	v_exp_f32_e32 v59, v59
	v_pk_add_f32 v[60:61], v[60:61], 1.0 op_sel_hi:[1,0]
	v_add_f32_e32 v59, 1.0, v59
	v_div_scale_f32 v71, s[18:19], v59, v59, v58
	v_rcp_f32_e32 v72, v71
	s_nop 0
	v_fma_f32 v73, -v71, v72, 1.0
	v_fmac_f32_e32 v72, v73, v72
	v_div_scale_f32 v73, vcc, v58, v59, v58
	v_mul_f32_e32 v74, v73, v72
	v_fma_f32 v76, -v71, v74, v73
	v_fmac_f32_e32 v74, v76, v72
	v_fma_f32 v71, -v71, v74, v73
	v_div_fmas_f32 v71, v71, v72, v74
	v_div_fixup_f32 v58, v71, v59, v58
	v_lshlrev_b32_e32 v59, 16, v67
	v_mul_f32_e32 v67, 0xbfb8aa3b, v59
	v_exp_f32_e32 v67, v67
	v_mul_f32_e32 v95, 0x3db504f3, v58
	v_lshlrev_b32_e32 v58, 16, v68
	v_mul_f32_e32 v58, 0xbfb8aa3b, v58
	v_add_f32_e32 v67, 1.0, v67
	v_div_scale_f32 v68, s[18:19], v67, v67, v59
	v_rcp_f32_e32 v71, v68
	v_exp_f32_e32 v58, v58
	v_fma_f32 v72, -v68, v71, 1.0
	v_fmac_f32_e32 v71, v72, v71
	v_div_scale_f32 v72, vcc, v59, v67, v59
	v_mul_f32_e32 v73, v72, v71
	v_fma_f32 v74, -v68, v73, v72
	v_fmac_f32_e32 v73, v74, v71
	v_fma_f32 v68, -v68, v73, v72
	v_div_fmas_f32 v68, v68, v71, v73
	v_div_fixup_f32 v59, v68, v67, v59
	v_mul_f32_e32 v96, 0x3db504f3, v59
	s_waitcnt vmcnt(1)
; template <int K, bool HG>
; __device__ void chunk_item(const Ctx& cx, CParamsPtr pp, int l, int item, char* shm) {
;     ...
;   auto prefetch = [&](int c) {
;     const size_t t0 = tb + (size_t)c * C;
;     const u16* rowq = p.proj + t0 * NP + qcol;
;     const u16* rowk = p.proj + t0 * NP + kcol;
;     const float* rowg = p.gla_a + t0 * 1024 + hd * 256;
; #pragma unroll
;     for (int i = 0; i < TPS; ++i) {
;       typedef const __attribute__((address_space(1))) char* gcp;
;       rq[i] = *(const __attribute__((address_space(1))) u16*)((gcp)opq(rowq + (size_t)i * NP) + lo2);
;       rk[i] = *(const __attribute__((address_space(1))) u16*)((gcp)opq(rowk + (size_t)i * NP) + lo2);
;       if (!HG) rg[i] = *(const __attribute__((address_space(1))) float*)((gcp)opq(rowg + (size_t)i * 1024) + lo4);
;     }
;     ...
;       if (HG) {
;         const float sg = 1.0f / (1.0f + __expf(-kraw));
;         const float f = fmaxf(lbv + (1.0f - lbv) * sg, 1e-12f);
;         gi = __logf(f);
;         kvv[i] = (1.0f - lbv) * (1.0f - sg);
	v_lshlrev_b32_e32 v59, 16, v66
	v_mul_f32_e32 v66, 0xbfb8aa3b, v64
	v_exp_f32_e32 v66, v66
	v_mul_f32_e32 v59, 0xbfb8aa3b, v59
	v_exp_f32_e32 v59, v59
	v_add_f32_e32 v66, 1.0, v66
	v_div_scale_f32 v67, s[18:19], v66, v66, v64
	s_cselect_b64 s[18:19], -1, 0
	v_rcp_f32_e32 v68, v67
	s_cmp_lg_u64 s[18:19], 0
	s_addc_u32 s18, s30, 0
	s_lshl_b32 s18, s18, 5
	s_add_i32 s74, s18, s27
	v_fma_f32 v71, -v67, v68, 1.0
	s_mul_i32 s19, s74, 0xc000
	v_fmac_f32_e32 v68, v71, v68
	v_div_scale_f32 v71, vcc, v64, v66, v64
	s_mul_hi_u32 s18, s74, 0xc000
	s_add_u32 s19, s20, s19
	v_mul_f32_e32 v72, v71, v68
	s_addc_u32 s33, s21, s18
	v_fma_f32 v73, -v67, v72, v71
	s_add_u32 s24, s19, s28
	v_fmac_f32_e32 v72, v73, v68
	s_addc_u32 s25, s33, 0
	v_fma_f32 v67, -v67, v72, v71
	s_add_u32 s18, s19, s29
	s_mov_b64 s[36:37], s[24:25]
	v_div_fmas_f32 v67, v67, v68, v72
	s_addc_u32 s19, s33, 0
	v_div_fixup_f32 v64, v67, v66, v64
	global_load_ushort v83, v42, s[36:37]
	s_mov_b64 s[36:37], s[18:19]
	v_mul_f32_e32 v97, 0x3db504f3, v64
	global_load_ushort v85, v42, s[36:37]
	s_add_u32 s36, s24, 0xc000
	s_addc_u32 s37, s25, 0
	v_pk_add_f32 v[58:59], v[58:59], 1.0 op_sel_hi:[1,0]
	global_load_ushort v81, v42, s[36:37]
	s_add_u32 s36, s18, 0xc000
	s_addc_u32 s37, s19, 0
	s_nop 0
	global_load_ushort v82, v42, s[36:37]
	s_add_u32 s36, s24, 0x18000
	s_addc_u32 s37, s25, 0
	s_nop 0
	global_load_ushort v78, v42, s[36:37]
	s_add_u32 s36, s18, 0x18000
	s_addc_u32 s37, s19, 0
	s_nop 0
	global_load_ushort v79, v42, s[36:37]
	s_add_u32 s36, s24, 0x24000
	s_addc_u32 s37, s25, 0
	s_nop 0
	global_load_ushort v76, v42, s[36:37]
	s_add_u32 s36, s18, 0x24000
	s_addc_u32 s37, s19, 0
	s_nop 0
	global_load_ushort v77, v42, s[36:37]
	s_add_u32 s36, s24, 0x30000
	s_addc_u32 s37, s25, 0
	s_nop 0
	global_load_ushort v73, v42, s[36:37]
	s_add_u32 s36, s18, 0x30000
	s_addc_u32 s37, s19, 0
	s_nop 0
	global_load_ushort v74, v42, s[36:37]
	s_add_u32 s36, s24, 0x3c000
	s_addc_u32 s37, s25, 0
	s_nop 0
	global_load_ushort v71, v42, s[36:37]
	s_add_u32 s36, s18, 0x3c000
	s_addc_u32 s37, s19, 0
	s_nop 0
	global_load_ushort v72, v42, s[36:37]
	s_add_u32 s36, s24, 0x48000
	s_addc_u32 s37, s25, 0
	s_nop 0
	global_load_ushort v67, v42, s[36:37]
	s_add_u32 s36, s18, 0x48000
	s_addc_u32 s37, s19, 0
	s_add_u32 s24, s24, 0x54000
	s_addc_u32 s25, s25, 0
	s_add_u32 s18, s18, 0x54000
	global_load_ushort v68, v42, s[36:37]
	s_addc_u32 s19, s19, 0
	global_load_ushort v64, v42, s[24:25]
	s_nop 0
	global_load_ushort v66, v42, s[18:19]
	v_div_scale_f32 v99, s[18:19], v59, v59, 1.0
	v_rcp_f32_e32 v100, v99
	v_add3_u32 v98, s34, v62, v63
	v_fma_f32 v101, -v99, v100, 1.0
	v_fmac_f32_e32 v100, v101, v100
	v_div_scale_f32 v101, vcc, 1.0, v59, 1.0
	v_mul_f32_e32 v102, v101, v100
	v_fma_f32 v103, -v99, v102, v101
	v_fmac_f32_e32 v102, v103, v100
	v_fma_f32 v99, -v99, v102, v101
	v_div_fmas_f32 v99, v99, v100, v102
	v_div_fixup_f32 v59, v99, v59, 1.0
	v_div_scale_f32 v99, s[18:19], v58, v58, 1.0
	v_rcp_f32_e32 v100, v99
	s_nop 0
	v_fma_f32 v101, -v99, v100, 1.0
	v_fmac_f32_e32 v100, v101, v100
	v_div_scale_f32 v101, vcc, 1.0, v58, 1.0
	v_mul_f32_e32 v102, v101, v100
	v_fma_f32 v103, -v99, v102, v101
	v_fmac_f32_e32 v102, v103, v100
	v_fma_f32 v99, -v99, v102, v101
	v_div_fmas_f32 v99, v99, v100, v102
	v_div_fixup_f32 v58, v99, v58, 1.0
	v_fma_f32 v99, v46, v58, v41
	v_max_f32_e32 v99, 0x2b8cbccc, v99
	v_cmp_gt_f32_e32 vcc, s83, v99
	s_nop 1
	v_cndmask_b32_e64 v100, 0, 32, vcc
	v_ldexp_f32 v99, v99, v100
	v_log_f32_e32 v99, v99
	s_nop 0
	v_mul_f32_e32 v100, 0x3f317217, v99
	v_fma_f32 v100, v99, s86, -v100
	v_fmac_f32_e32 v100, 0x3377d1cf, v99
	v_fmac_f32_e32 v100, 0x3f317217, v99
	v_cmp_lt_f32_e64 s[18:19], |v99|, s87
	s_nop 1
	v_cndmask_b32_e64 v99, v99, v100, s[18:19]
	v_cndmask_b32_e32 v100, 0, v165, vcc
	v_sub_f32_e32 v99, v99, v100
	v_fma_f32 v100, v46, v59, v41
	v_max_f32_e32 v100, 0x2b8cbccc, v100
	v_cmp_gt_f32_e32 vcc, s83, v100
	v_pk_add_f32 v[58:59], v[58:59], 1.0 op_sel_hi:[1,0] neg_lo:[1,0] neg_hi:[1,0]
	s_nop 0
	v_cndmask_b32_e64 v101, 0, 32, vcc
	v_ldexp_f32 v100, v100, v101
	v_log_f32_e32 v100, v100
	v_pk_mul_f32 v[58:59], v[46:47], v[58:59]
	v_mul_f32_e32 v101, 0x3f317217, v100
	v_fma_f32 v101, v100, s86, -v101
	v_fmac_f32_e32 v101, 0x3377d1cf, v100
	v_fmac_f32_e32 v101, 0x3f317217, v100
	v_cmp_lt_f32_e64 s[18:19], |v100|, s87
	s_nop 1
	v_cndmask_b32_e64 v100, v100, v101, s[18:19]
	v_cndmask_b32_e32 v101, 0, v165, vcc
	v_sub_f32_e32 v100, v100, v101
	v_div_scale_f32 v101, s[18:19], v61, v61, 1.0
	v_rcp_f32_e32 v102, v101
	s_nop 0
	v_fma_f32 v103, -v101, v102, 1.0
	v_fmac_f32_e32 v102, v103, v102
	v_div_scale_f32 v103, vcc, 1.0, v61, 1.0
	v_mul_f32_e32 v104, v103, v102
	v_fma_f32 v105, -v101, v104, v103
	v_fmac_f32_e32 v104, v105, v102
	v_fma_f32 v101, -v101, v104, v103
	v_div_fmas_f32 v101, v101, v102, v104
	v_div_fixup_f32 v61, v101, v61, 1.0
	v_div_scale_f32 v101, s[18:19], v60, v60, 1.0
	v_rcp_f32_e32 v102, v101
	s_nop 0
	v_fma_f32 v103, -v101, v102, 1.0
	v_fmac_f32_e32 v102, v103, v102
	v_div_scale_f32 v103, vcc, 1.0, v60, 1.0
	v_mul_f32_e32 v104, v103, v102
	v_fma_f32 v105, -v101, v104, v103
	v_fmac_f32_e32 v104, v105, v102
	v_fma_f32 v101, -v101, v104, v103
	v_div_fmas_f32 v101, v101, v102, v104
	v_div_fixup_f32 v60, v101, v60, 1.0
	v_fma_f32 v101, v46, v60, v41
	v_max_f32_e32 v101, 0x2b8cbccc, v101
	v_cmp_gt_f32_e32 vcc, s83, v101
	s_nop 1
	v_cndmask_b32_e64 v102, 0, 32, vcc
	v_ldexp_f32 v101, v101, v102
	v_log_f32_e32 v101, v101
	s_nop 0
	v_mul_f32_e32 v102, 0x3f317217, v101
	v_fma_f32 v102, v101, s86, -v102
	v_fmac_f32_e32 v102, 0x3377d1cf, v101
	v_fmac_f32_e32 v102, 0x3f317217, v101
; template <int K, bool HG>
; __device__ void chunk_item(const Ctx& cx, CParamsPtr pp, int l, int item, char* shm) {
;     ...
;       if (HG) {
;         const float sg = 1.0f / (1.0f + __expf(-kraw));
;         const float f = fmaxf(lbv + (1.0f - lbv) * sg, 1e-12f);
;         gi = __logf(f);
;         kvv[i] = (1.0f - lbv) * (1.0f - sg);
;         qvv[i] = qraw / (1.0f + __expf(-qraw)) * 0.08838834764831845f;
;       } else {
;         gi = rg[i];
;         kvv[i] = kraw;
;         qvv[i] = qraw * 0.0625f;
;       }
;       run += gi;
;       bl[i] = run;
;     }
;     prefetch(c + 1 < NCH ? c + 1 : c);
;     float offs = 0.f, total = 0.f;
; #pragma unroll
;     for (int j = 0; j < NSEG; ++j) {
;       const float rj = shi(run, (lane % LPS) + LPS * j);
;       total += rj;
;       if (j < seg) offs += rj;
;     }
	v_cmp_lt_f32_e64 s[18:19], |v101|, s87
	s_nop 1
	v_cndmask_b32_e64 v101, v101, v102, s[18:19]
	v_cndmask_b32_e32 v102, 0, v165, vcc
	v_sub_f32_e32 v101, v101, v102
	v_fma_f32 v102, v46, v61, v41
	v_max_f32_e32 v102, 0x2b8cbccc, v102
	v_cmp_gt_f32_e32 vcc, s83, v102
	v_pk_add_f32 v[60:61], v[60:61], 1.0 op_sel_hi:[1,0] neg_lo:[1,0] neg_hi:[1,0]
	s_nop 0
	v_cndmask_b32_e64 v103, 0, 32, vcc
	v_ldexp_f32 v102, v102, v103
	v_log_f32_e32 v102, v102
	v_pk_mul_f32 v[60:61], v[46:47], v[60:61]
	v_mul_f32_e32 v103, 0x3f317217, v102
	v_fma_f32 v103, v102, s86, -v103
	v_fmac_f32_e32 v103, 0x3377d1cf, v102
	v_fmac_f32_e32 v103, 0x3f317217, v102
	v_cmp_lt_f32_e64 s[18:19], |v102|, s87
	s_nop 1
	v_cndmask_b32_e64 v102, v102, v103, s[18:19]
	v_cndmask_b32_e32 v103, 0, v165, vcc
	v_sub_f32_e32 v104, v102, v103
	v_div_scale_f32 v102, s[18:19], v57, v57, 1.0
	v_rcp_f32_e32 v103, v102
	s_nop 0
	v_fma_f32 v105, -v102, v103, 1.0
	v_fmac_f32_e32 v103, v105, v103
	v_div_scale_f32 v105, vcc, 1.0, v57, 1.0
	v_mul_f32_e32 v106, v105, v103
	v_fma_f32 v107, -v102, v106, v105
	v_fmac_f32_e32 v106, v107, v103
	v_fma_f32 v102, -v102, v106, v105
	v_div_fmas_f32 v102, v102, v103, v106
	v_div_fixup_f32 v57, v102, v57, 1.0
	v_div_scale_f32 v102, s[18:19], v56, v56, 1.0
	v_rcp_f32_e32 v103, v102
	s_nop 0
	v_fma_f32 v105, -v102, v103, 1.0
	v_fmac_f32_e32 v103, v105, v103
	v_div_scale_f32 v105, vcc, 1.0, v56, 1.0
	v_mul_f32_e32 v106, v105, v103
	v_fma_f32 v107, -v102, v106, v105
	v_fmac_f32_e32 v106, v107, v103
	v_fma_f32 v102, -v102, v106, v105
	v_div_fmas_f32 v102, v102, v103, v106
	v_div_fixup_f32 v56, v102, v56, 1.0
	v_fma_f32 v102, v46, v56, v41
	v_max_f32_e32 v102, 0x2b8cbccc, v102
	v_cmp_gt_f32_e32 vcc, s83, v102
	s_nop 1
	v_cndmask_b32_e64 v103, 0, 32, vcc
	v_ldexp_f32 v102, v102, v103
	v_log_f32_e32 v102, v102
	s_nop 0
	v_mul_f32_e32 v103, 0x3f317217, v102
	v_fma_f32 v103, v102, s86, -v103
	v_fmac_f32_e32 v103, 0x3377d1cf, v102
	v_fmac_f32_e32 v103, 0x3f317217, v102
	v_cmp_lt_f32_e64 s[18:19], |v102|, s87
	s_nop 1
	v_cndmask_b32_e64 v102, v102, v103, s[18:19]
	v_cndmask_b32_e32 v103, 0, v165, vcc
	v_sub_f32_e32 v105, v102, v103
	v_fma_f32 v102, v46, v57, v41
	v_max_f32_e32 v102, 0x2b8cbccc, v102
	v_cmp_gt_f32_e32 vcc, s83, v102
	v_pk_add_f32 v[56:57], v[56:57], 1.0 op_sel_hi:[1,0] neg_lo:[1,0] neg_hi:[1,0]
	s_nop 0
	v_cndmask_b32_e64 v103, 0, 32, vcc
	v_ldexp_f32 v102, v102, v103
	v_log_f32_e32 v102, v102
	v_pk_mul_f32 v[56:57], v[46:47], v[56:57]
	v_mul_f32_e32 v103, 0x3f317217, v102
	v_fma_f32 v103, v102, s86, -v103
	v_fmac_f32_e32 v103, 0x3377d1cf, v102
	v_fmac_f32_e32 v103, 0x3f317217, v102
	v_cmp_lt_f32_e64 s[18:19], |v102|, s87
	s_nop 1
	v_cndmask_b32_e64 v102, v102, v103, s[18:19]
	v_cndmask_b32_e32 v103, 0, v165, vcc
	v_sub_f32_e32 v106, v102, v103
	v_div_scale_f32 v102, s[18:19], v1, v1, 1.0
	v_rcp_f32_e32 v103, v102
	s_nop 0
	v_fma_f32 v107, -v102, v103, 1.0
	v_fmac_f32_e32 v103, v107, v103
	v_div_scale_f32 v107, vcc, 1.0, v1, 1.0
	v_mul_f32_e32 v108, v107, v103
	v_fma_f32 v109, -v102, v108, v107
	v_fmac_f32_e32 v108, v109, v103
	v_fma_f32 v102, -v102, v108, v107
	v_div_fmas_f32 v102, v102, v103, v108
	v_div_fixup_f32 v1, v102, v1, 1.0
	v_div_scale_f32 v102, s[18:19], v0, v0, 1.0
	v_rcp_f32_e32 v103, v102
	s_nop 0
	v_fma_f32 v107, -v102, v103, 1.0
	v_fmac_f32_e32 v103, v107, v103
	v_div_scale_f32 v107, vcc, 1.0, v0, 1.0
	v_mul_f32_e32 v108, v107, v103
	v_fma_f32 v109, -v102, v108, v107
	v_fmac_f32_e32 v108, v109, v103
	v_fma_f32 v102, -v102, v108, v107
	v_div_fmas_f32 v102, v102, v103, v108
	v_div_fixup_f32 v0, v102, v0, 1.0
	v_fma_f32 v102, v46, v0, v41
	v_max_f32_e32 v102, 0x2b8cbccc, v102
	v_cmp_gt_f32_e32 vcc, s83, v102
	s_nop 1
	v_cndmask_b32_e64 v103, 0, 32, vcc
	v_ldexp_f32 v102, v102, v103
	v_log_f32_e32 v102, v102
	s_nop 0
	v_mul_f32_e32 v103, 0x3f317217, v102
	v_fma_f32 v103, v102, s86, -v103
	v_fmac_f32_e32 v103, 0x3377d1cf, v102
	v_fmac_f32_e32 v103, 0x3f317217, v102
	v_cmp_lt_f32_e64 s[18:19], |v102|, s87
	s_nop 1
	v_cndmask_b32_e64 v102, v102, v103, s[18:19]
	v_cndmask_b32_e32 v103, 0, v165, vcc
	v_sub_f32_e32 v102, v102, v103
	v_add_f32_e32 v107, 0, v102
	v_fma_f32 v102, v46, v1, v41
	v_max_f32_e32 v102, 0x2b8cbccc, v102
	v_cmp_gt_f32_e32 vcc, s83, v102
	v_pk_add_f32 v[0:1], v[0:1], 1.0 op_sel_hi:[1,0] neg_lo:[1,0] neg_hi:[1,0]
	s_nop 0
	v_cndmask_b32_e64 v103, 0, 32, vcc
	v_ldexp_f32 v102, v102, v103
	v_log_f32_e32 v102, v102
	s_nop 0
	v_mul_f32_e32 v103, 0x3f317217, v102
	v_fma_f32 v103, v102, s86, -v103
	v_fmac_f32_e32 v103, 0x3377d1cf, v102
	v_fmac_f32_e32 v103, 0x3f317217, v102
	v_cmp_lt_f32_e64 s[18:19], |v102|, s87
	s_nop 1
	v_cndmask_b32_e64 v102, v102, v103, s[18:19]
	v_cndmask_b32_e32 v103, 0, v165, vcc
	v_sub_f32_e32 v108, v102, v103
	v_pk_mul_f32 v[102:103], v[46:47], v[0:1]
	v_add_f32_e32 v1, v108, v107
	v_add_f32_e32 v108, v105, v1
	v_add_f32_e32 v106, v106, v108
	v_add_f32_e32 v109, v101, v106
	v_add_f32_e32 v110, v104, v109
	v_add_f32_e32 v99, v99, v110
	v_add_f32_e32 v111, v100, v99
	ds_bpermute_b32 v0, v48, v111
	ds_bpermute_b32 v101, v86, v111
	s_waitcnt lgkmcnt(1)
; template <int K, bool HG>
; __device__ void chunk_item(const Ctx& cx, CParamsPtr pp, int l, int item, char* shm) {
;     ...
;     for (int j = 0; j < NSEG; ++j) {
;       const float rj = shi(run, (lane % LPS) + LPS * j);
;       total += rj;
;       if (j < seg) offs += rj;
;     }
;     uint32_t kpw[TPS / 2];
;     float kpv[TPS];
;     const float etot = __expf(total);
; #pragma unroll
;     for (int i = 0; i < TPS; ++i) {
;       const float bb = offs + bl[i];
;       const int t = seg * TPS + i;
;       const float eq = __expf(bb), ek = __expf(fminf(-bb, 85.0f)), ekp = etot * ek;
;       *(u16*)(QT + t * RS + kc * 2) = f2b(qvv[i] * eq);
;       *(u16*)(KT + t * RS + kc * 2) = f2b(kvv[i] * ek);
;       kpv[i] = kvv[i] * ekp;
;     }
; #pragma unroll
;     for (int i = 0; i < TPS / 2; ++i) kpw[i] = pack2(kpv[2 * i], kpv[2 * i + 1]);
; #pragma unroll
;     for (int i = 0; i < TPS / 8; ++i)
;       *(uint4*)(KP + kc * 80 + seg * TPS * 2 + i * 16) = make_uint4(kpw[i * 4], kpw[i * 4 + 1], kpw[i * 4 + 2], kpw[i * 4 + 3]);
;     if (seg == 0) EB[kc] = etot;
	v_add_f32_e32 v0, 0, v0
	v_cndmask_b32_e64 v100, v0, 0, s[16:17]
	s_waitcnt lgkmcnt(0)
	v_add_f32_e32 v0, v0, v101
	v_add_f32_e32 v101, v100, v101
	v_cndmask_b32_e64 v100, v100, v101, s[4:5]
	ds_bpermute_b32 v101, v87, v111
	s_waitcnt lgkmcnt(0)
	v_add_f32_e32 v0, v0, v101
	v_add_f32_e32 v101, v100, v101
	v_cndmask_b32_e64 v112, v100, v101, s[6:7]
	ds_bpermute_b32 v100, v88, v111
	v_add_f32_e32 v1, v1, v112
	s_waitcnt lgkmcnt(0)
	v_add_f32_e32 v0, v0, v100
	v_add_f32_e32 v100, v107, v112
	v_mul_f32_e32 v101, 0x3fb8aa3b, v100
	v_exp_f32_e32 v101, v101
	v_min_f32_e64 v100, -v100, s88
	v_mul_f32_e32 v100, 0x3fb8aa3b, v100
	v_exp_f32_e32 v100, v100
	v_mul_f32_e32 v2, v2, v101
	v_cvt_pk_bf16_f32 v2, v2, s0
	ds_write_b16 v98, v2
	v_mul_f32_e32 v2, v102, v100
	v_cvt_pk_bf16_f32 v2, v2, s0
	ds_write_b16 v98, v2 offset:8704
	v_mul_f32_e32 v2, 0x3fb8aa3b, v1
	v_min_f32_e64 v1, -v1, s88
	v_mul_f32_e32 v0, 0x3fb8aa3b, v0
	v_mul_f32_e32 v1, 0x3fb8aa3b, v1
	v_exp_f32_e32 v0, v0
	v_exp_f32_e32 v2, v2
	v_exp_f32_e32 v101, v1
	s_nop 0
	v_pk_mul_f32 v[104:105], v[0:1], v[100:101] op_sel_hi:[0,1]
	v_mul_f32_e32 v1, v49, v2
	v_cvt_pk_bf16_f32 v1, v1, s0
	ds_write_b16 v98, v1 offset:272
	v_mul_f32_e32 v1, v103, v101
	v_cvt_pk_bf16_f32 v1, v1, s0
	ds_write_b16 v98, v1 offset:8976
	v_add_f32_e32 v1, v108, v112
	v_mul_f32_e32 v2, 0x3fb8aa3b, v1
	v_exp_f32_e32 v2, v2
	v_min_f32_e64 v1, -v1, s88
	v_mul_f32_e32 v1, 0x3fb8aa3b, v1
	v_pk_mul_f32 v[100:101], v[102:103], v[104:105]
	v_exp_f32_e32 v102, v1
	v_mul_f32_e32 v1, v92, v2
	v_cvt_pk_bf16_f32 v1, v1, s0
	ds_write_b16 v98, v1 offset:544
	v_mul_f32_e32 v1, v56, v102
	v_cvt_pk_bf16_f32 v1, v1, s0
	ds_write_b16 v98, v1 offset:9248
	v_add_f32_e32 v1, v106, v112
	v_mul_f32_e32 v2, 0x3fb8aa3b, v1
	v_min_f32_e64 v1, -v1, s88
	v_mul_f32_e32 v1, 0x3fb8aa3b, v1
	v_exp_f32_e32 v2, v2
	v_exp_f32_e32 v103, v1
	s_nop 0
	v_pk_mul_f32 v[104:105], v[0:1], v[102:103] op_sel_hi:[0,1]
	v_mul_f32_e32 v1, v93, v2
	v_cvt_pk_bf16_f32 v1, v1, s0
	ds_write_b16 v98, v1 offset:816
	v_mul_f32_e32 v1, v57, v103
	v_cvt_pk_bf16_f32 v1, v1, s0
	ds_write_b16 v98, v1 offset:9520
	v_add_f32_e32 v1, v109, v112
	v_mul_f32_e32 v2, 0x3fb8aa3b, v1
	v_exp_f32_e32 v2, v2
	v_min_f32_e64 v1, -v1, s88
	v_mul_f32_e32 v1, 0x3fb8aa3b, v1
	v_pk_mul_f32 v[92:93], v[56:57], v[104:105]
	v_exp_f32_e32 v56, v1
	v_mul_f32_e32 v1, v94, v2
	v_cvt_pk_bf16_f32 v1, v1, s0
	ds_write_b16 v98, v1 offset:1088
	v_mul_f32_e32 v1, v60, v56
	v_cvt_pk_bf16_f32 v1, v1, s0
	ds_write_b16 v98, v1 offset:9792
	v_add_f32_e32 v1, v110, v112
	v_mul_f32_e32 v2, 0x3fb8aa3b, v1
	v_min_f32_e64 v1, -v1, s88
	v_mul_f32_e32 v1, 0x3fb8aa3b, v1
	v_exp_f32_e32 v2, v2
	v_exp_f32_e32 v57, v1
	s_nop 0
	v_pk_mul_f32 v[102:103], v[0:1], v[56:57] op_sel_hi:[0,1]
	v_mul_f32_e32 v1, v95, v2
	v_cvt_pk_bf16_f32 v1, v1, s0
	ds_write_b16 v98, v1 offset:1360
	v_mul_f32_e32 v1, v61, v57
	v_cvt_pk_bf16_f32 v1, v1, s0
	ds_write_b16 v98, v1 offset:10064
	v_add_f32_e32 v1, v99, v112
	v_mul_f32_e32 v2, 0x3fb8aa3b, v1
	v_exp_f32_e32 v2, v2
	v_min_f32_e64 v1, -v1, s88
	v_mul_f32_e32 v1, 0x3fb8aa3b, v1
	v_exp_f32_e32 v56, v1
	v_mul_f32_e32 v1, v96, v2
	v_cvt_pk_bf16_f32 v1, v1, s0
	ds_write_b16 v98, v1 offset:1632
	v_mul_f32_e32 v1, v58, v56
	v_cvt_pk_bf16_f32 v1, v1, s0
	ds_write_b16 v98, v1 offset:10336
	v_add_f32_e32 v1, v111, v112
	v_mul_f32_e32 v2, 0x3fb8aa3b, v1
	v_min_f32_e64 v1, -v1, s88
	v_mul_f32_e32 v1, 0x3fb8aa3b, v1
	v_exp_f32_e32 v2, v2
	v_exp_f32_e32 v57, v1
	v_pk_mul_f32 v[60:61], v[60:61], v[102:103]
	v_pk_mul_f32 v[94:95], v[0:1], v[56:57] op_sel_hi:[0,1]
	v_mul_f32_e32 v1, v97, v2
	v_cvt_pk_bf16_f32 v1, v1, s0
	ds_write_b16 v98, v1 offset:1904
	v_mul_f32_e32 v1, v59, v57
	v_cvt_pk_bf16_f32 v1, v1, s0
	ds_write_b16 v98, v1 offset:10608
	v_pk_mul_f32 v[94:95], v[58:59], v[94:95]
	v_add_u32_e32 v1, s34, v69
	v_cvt_pk_bf16_f32 v56, v100, v101
	v_cvt_pk_bf16_f32 v57, v92, v93
	v_cvt_pk_bf16_f32 v58, v60, v61
	v_cvt_pk_bf16_f32 v59, v94, v95
	v_add_u32_e32 v2, v1, v80
	ds_write_b128 v2, v[56:59] offset:17408
	s_and_saveexec_b64 s[18:19], s[16:17]
	s_cbranch_execz .LBB0_191
	v_add_u32_e32 v1, v1, v84
	ds_write_b32 v1, v0 offset:37888
	s_branch .LBB0_191

; template <int K, bool HG>
; __device__ void chunk_item(const Ctx& cx, CParamsPtr pp, int l, int item, char* shm) {
;     ...
;   auto prefetch = [&](int c) {
;     const size_t t0 = tb + (size_t)c * C;
;     const u16* rowq = p.proj + t0 * NP + qcol;
;     const u16* rowk = p.proj + t0 * NP + kcol;
;     const float* rowg = p.gla_a + t0 * 1024 + hd * 256;
; #pragma unroll
;     for (int i = 0; i < TPS; ++i) {
;       typedef const __attribute__((address_space(1))) char* gcp;
;       rq[i] = *(const __attribute__((address_space(1))) u16*)((gcp)opq(rowq + (size_t)i * NP) + lo2);
;       rk[i] = *(const __attribute__((address_space(1))) u16*)((gcp)opq(rowk + (size_t)i * NP) + lo2);
;       if (!HG) rg[i] = *(const __attribute__((address_space(1))) float*)((gcp)opq(rowg + (size_t)i * 1024) + lo4);
;     }
;     ...
;         gi = rg[i];
;         kvv[i] = kraw;
;         qvv[i] = qraw * 0.0625f;
;       }
;       run += gi;
;       bl[i] = run;
;     }
.LBB0_202:
	s_and_b32 s12, s27, 0x10000
	s_add_i32 s28, s12, 0
	s_cmp_lg_u32 s14, 0xf80000
	s_cselect_b64 s[12:13], -1, 0
	s_cmp_lg_u64 s[12:13], 0
	s_addc_u32 s12, s22, 0
	s_lshl_b32 s12, s12, 5
	s_add_u32 s12, s16, s12
	s_addc_u32 s13, s17, 0
	s_mul_i32 s18, s13, 0xc000
	s_mul_hi_u32 s19, s12, 0xc000
	s_add_i32 s19, s19, s18
	s_mul_i32 s18, s12, 0xc000
	s_add_u32 s18, s25, s18
	s_addc_u32 s19, s26, s19
	s_add_u32 s30, s18, 0x800
	s_addc_u32 s31, s19, 0
	s_lshl_b64 s[20:21], s[12:13], 12
	s_mov_b64 s[34:35], s[18:19]
	s_add_u32 s20, s23, s20
	v_lshlrev_b32_e32 v0, 16, v123
	global_load_ushort v123, v112, s[34:35]
	s_addc_u32 s21, s24, s21
	v_add_f32_e32 v109, 0, v124
	global_load_ushort v179, v112, s[30:31]
	s_mov_b64 s[30:31], s[20:21]
	v_mul_f32_e32 v107, 0x3d800000, v0
	global_load_dword v124, v114, s[30:31]
	s_add_u32 s30, s18, 0xc000
	s_addc_u32 s31, s19, 0
	v_lshlrev_b32_e32 v0, 16, v125
	global_load_ushort v125, v112, s[30:31]
	s_add_u32 s30, s18, 0xc800
	s_addc_u32 s31, s19, 0
	v_add_f32_e32 v108, v126, v109
	global_load_ushort v180, v112, s[30:31]
	s_add_u32 s30, s20, 0x1000
	s_addc_u32 s31, s21, 0
	v_mul_f32_e32 v106, 0x3d800000, v0
	global_load_dword v126, v114, s[30:31]
	s_add_u32 s30, s18, 0x18000
	s_addc_u32 s31, s19, 0
	v_lshlrev_b32_e32 v0, 16, v127
	global_load_ushort v127, v112, s[30:31]
	s_add_u32 s30, s18, 0x18800
	s_addc_u32 s31, s19, 0
	v_add_f32_e32 v105, v132, v108
	global_load_ushort v181, v112, s[30:31]
	s_add_u32 s30, s20, 0x2000
	s_addc_u32 s31, s21, 0
	v_mul_f32_e32 v103, 0x3d800000, v0
	global_load_dword v132, v114, s[30:31]
	s_add_u32 s30, s18, 0x24000
	s_addc_u32 s31, s19, 0
	v_lshlrev_b32_e32 v0, 16, v133
	global_load_ushort v133, v112, s[30:31]
	s_add_u32 s30, s18, 0x24800
	s_addc_u32 s31, s19, 0
	v_add_f32_e32 v104, v134, v105
	global_load_ushort v182, v112, s[30:31]
	s_add_u32 s30, s20, 0x3000
	s_addc_u32 s31, s21, 0
	v_mul_f32_e32 v102, 0x3d800000, v0
	global_load_dword v134, v114, s[30:31]
	s_add_u32 s30, s18, 0x30000
	s_addc_u32 s31, s19, 0
	v_lshlrev_b32_e32 v0, 16, v135
	global_load_ushort v135, v112, s[30:31]
	s_add_u32 s30, s18, 0x30800
	s_addc_u32 s31, s19, 0
	v_add_f32_e32 v101, v136, v104
	global_load_ushort v183, v112, s[30:31]
	s_add_u32 s30, s20, 0x4000
	s_addc_u32 s31, s21, 0
	v_mul_f32_e32 v99, 0x3d800000, v0
	global_load_dword v136, v114, s[30:31]
	s_add_u32 s30, s18, 0x3c000
	s_addc_u32 s31, s19, 0
	v_lshlrev_b32_e32 v0, 16, v137
	global_load_ushort v137, v112, s[30:31]
	s_add_u32 s30, s18, 0x3c800
	s_addc_u32 s31, s19, 0
	v_add_f32_e32 v100, v139, v101
	global_load_ushort v184, v112, s[30:31]
	s_add_u32 s30, s20, 0x5000
	s_addc_u32 s31, s21, 0
	v_mul_f32_e32 v98, 0x3d800000, v0
	global_load_dword v139, v114, s[30:31]
	s_add_u32 s30, s18, 0x48000
	s_addc_u32 s31, s19, 0
	v_lshlrev_b32_e32 v0, 16, v141
	global_load_ushort v141, v112, s[30:31]
	s_add_u32 s30, s18, 0x48800
	s_addc_u32 s31, s19, 0
	v_add_f32_e32 v97, v144, v100
	global_load_ushort v185, v112, s[30:31]
	s_add_u32 s30, s20, 0x6000
	s_addc_u32 s31, s21, 0
	v_mul_f32_e32 v95, 0x3d800000, v0
	global_load_dword v144, v114, s[30:31]
	s_add_u32 s30, s18, 0x54000
	s_addc_u32 s31, s19, 0
	v_lshlrev_b32_e32 v0, 16, v146
	global_load_ushort v146, v112, s[30:31]
	s_add_u32 s30, s18, 0x54800
	s_addc_u32 s31, s19, 0
	v_add_f32_e32 v96, v147, v97
	global_load_ushort v186, v112, s[30:31]
	s_add_u32 s30, s20, 0x7000
	s_addc_u32 s31, s21, 0
	v_mul_f32_e32 v94, 0x3d800000, v0
	global_load_dword v147, v114, s[30:31]
	s_add_u32 s30, s18, 0x60000
	s_addc_u32 s31, s19, 0
	v_lshlrev_b32_e32 v0, 16, v148
	global_load_ushort v148, v112, s[30:31]
	s_add_u32 s30, s18, 0x60800
	s_addc_u32 s31, s19, 0
	v_add_f32_e32 v93, v149, v96
	global_load_ushort v187, v112, s[30:31]
	s_add_u32 s30, s20, 0x8000
	s_addc_u32 s31, s21, 0
	v_mul_f32_e32 v91, 0x3d800000, v0
	global_load_dword v149, v114, s[30:31]
	s_add_u32 s30, s18, 0x6c000
	s_addc_u32 s31, s19, 0
	v_lshlrev_b32_e32 v0, 16, v150
	global_load_ushort v150, v112, s[30:31]
	s_add_u32 s30, s18, 0x6c800
	s_addc_u32 s31, s19, 0
	v_add_f32_e32 v92, v151, v93
	global_load_ushort v188, v112, s[30:31]
	s_add_u32 s30, s20, 0x9000
	s_addc_u32 s31, s21, 0
	v_mul_f32_e32 v90, 0x3d800000, v0
	global_load_dword v151, v114, s[30:31]
	s_add_u32 s30, s18, 0x78000
	s_addc_u32 s31, s19, 0
	v_lshlrev_b32_e32 v0, 16, v152
	global_load_ushort v152, v112, s[30:31]
	s_add_u32 s30, s18, 0x78800
	s_addc_u32 s31, s19, 0
	v_add_f32_e32 v89, v153, v92
	global_load_ushort v189, v112, s[30:31]
	s_add_u32 s30, s20, 0xa000
	s_addc_u32 s31, s21, 0
	v_mul_f32_e32 v87, 0x3d800000, v0
	global_load_dword v153, v114, s[30:31]
	s_add_u32 s30, s18, 0x84000
	s_addc_u32 s31, s19, 0
	v_lshlrev_b32_e32 v0, 16, v154
	global_load_ushort v154, v112, s[30:31]
	s_add_u32 s30, s18, 0x84800
	s_addc_u32 s31, s19, 0
	v_add_f32_e32 v88, v156, v89
	global_load_ushort v190, v112, s[30:31]
	s_add_u32 s30, s20, 0xb000
	s_addc_u32 s31, s21, 0
	v_mul_f32_e32 v86, 0x3d800000, v0
	global_load_dword v156, v114, s[30:31]
	s_add_u32 s30, s18, 0x90000
	s_addc_u32 s31, s19, 0
	v_lshlrev_b32_e32 v0, 16, v157
	global_load_ushort v157, v112, s[30:31]
	s_add_u32 s30, s18, 0x90800
	s_addc_u32 s31, s19, 0
	v_add_f32_e32 v85, v160, v88
	global_load_ushort v191, v112, s[30:31]
	s_add_u32 s30, s20, 0xc000
	s_addc_u32 s31, s21, 0
	v_mul_f32_e32 v83, 0x3d800000, v0
	global_load_dword v160, v114, s[30:31]
	s_add_u32 s30, s18, 0x9c000
	s_addc_u32 s31, s19, 0
	v_lshlrev_b32_e32 v0, 16, v168
	global_load_ushort v168, v112, s[30:31]
	s_add_u32 s30, s18, 0x9c800
	s_addc_u32 s31, s19, 0
	v_add_f32_e32 v84, v172, v85
	global_load_ushort v192, v112, s[30:31]
	s_add_u32 s30, s20, 0xd000
	s_addc_u32 s31, s21, 0
	v_mul_f32_e32 v82, 0x3d800000, v0
	global_load_dword v172, v114, s[30:31]
	s_add_u32 s30, s18, 0xa8000
	s_addc_u32 s31, s19, 0
	v_lshlrev_b32_e32 v0, 16, v174
	global_load_ushort v174, v112, s[30:31]
	s_add_u32 s30, s18, 0xa8800
	s_addc_u32 s31, s19, 0
	v_add_f32_e32 v81, v175, v84
	v_lshl_add_u64 v[110:111], s[30:31], 0, v[112:113]
	s_add_u32 s30, s20, 0xe000
	s_addc_u32 s31, s21, 0
	v_mul_f32_e32 v79, 0x3d800000, v0
	v_lshlrev_b32_e32 v0, 16, v177
	s_waitcnt vmcnt(44)
; template <int K, bool HG>
; __device__ void chunk_item(const Ctx& cx, CParamsPtr pp, int l, int item, char* shm) {
;     ...
;     for (int j = 0; j < NSEG; ++j) {
;       const float rj = shi(run, (lane % LPS) + LPS * j);
;       total += rj;
;       if (j < seg) offs += rj;
;     }
;     uint32_t kpw[TPS / 2];
;     float kpv[TPS];
;     const float etot = __expf(total);
; #pragma unroll
;     for (int i = 0; i < TPS; ++i) {
;       const float bb = offs + bl[i];
;       const int t = seg * TPS + i;
;       const float eq = __expf(bb), ek = __expf(fminf(-bb, 85.0f)), ekp = etot * ek;
;       *(u16*)(QT + t * RS + kc * 2) = f2b(qvv[i] * eq);
;       *(u16*)(KT + t * RS + kc * 2) = f2b(kvv[i] * ek);
;       kpv[i] = kvv[i] * ekp;
	v_add_f32_e32 v80, v178, v81
	global_load_ushort v193, v[110:111], off
	v_mul_f32_e32 v2, 0x3d800000, v0
	v_lshl_add_u64 v[110:111], s[30:31], 0, v[114:115]
	s_add_u32 s30, s18, 0xb4000
	ds_bpermute_b32 v0, v143, v80
	s_addc_u32 s31, s19, 0
	s_add_u32 s18, s18, 0xb4800
	global_load_dword v175, v[110:111], off
	s_addc_u32 s19, s19, 0
	global_load_ushort v177, v112, s[30:31]
	s_waitcnt lgkmcnt(0)
	v_add_f32_e32 v0, 0, v0
	global_load_ushort v194, v112, s[18:19]
	s_add_u32 s18, s20, 0xf000
	s_addc_u32 s19, s21, 0
	v_cndmask_b32_e64 v196, v0, 0, vcc
	v_add_f32_e32 v109, v109, v196
	global_load_dword v178, v114, s[18:19]
	v_mul_f32_e32 v110, 0x3fb8aa3b, v109
	ds_bpermute_b32 v195, v169, v80
	v_exp_f32_e32 v111, v110
	v_min_f32_e64 v109, -v109, s88
	v_mul_f32_e32 v109, 0x3fb8aa3b, v109
	v_exp_f32_e32 v110, v109
	v_mul_f32_e32 v107, v107, v111
	s_waitcnt lgkmcnt(0)
	v_add_f32_e32 v0, v0, v195
	v_cvt_pk_bf16_f32 v107, v107, s0
	v_add3_u32 v195, s28, v122, v145
	ds_write_b16 v195, v107
	v_add_f32_e32 v107, v108, v196
	v_mul_f32_e32 v108, 0x3fb8aa3b, v107
	v_exp_f32_e32 v108, v108
	v_min_f32_e64 v107, -v107, s88
	v_mul_f32_e32 v107, 0x3fb8aa3b, v107
	v_exp_f32_e32 v111, v107
	v_mul_f32_e32 v106, v106, v108
	v_cvt_pk_bf16_f32 v106, v106, s0
	ds_write_b16 v195, v106 offset:528
	v_lshlrev_b32_e32 v106, 16, v78
	v_and_b32_e32 v107, 0xffff0000, v78
	v_mul_f32_e32 v78, v110, v106
	v_cvt_pk_bf16_f32 v78, v78, s0
	ds_write_b16 v195, v78 offset:16896
	v_mul_f32_e32 v78, v111, v107
	v_cvt_pk_bf16_f32 v78, v78, s0
	v_mul_f32_e32 v0, 0x3fb8aa3b, v0
	ds_write_b16 v195, v78 offset:17424
	v_add_f32_e32 v78, v105, v196
	v_exp_f32_e32 v0, v0
	v_mul_f32_e32 v105, 0x3fb8aa3b, v78
	v_exp_f32_e32 v105, v105
	v_min_f32_e64 v78, -v78, s88
	v_pk_mul_f32 v[108:109], v[0:1], v[110:111] op_sel_hi:[0,1]
	v_mul_f32_e32 v78, 0x3fb8aa3b, v78
	v_pk_mul_f32 v[106:107], v[108:109], v[106:107]
	v_exp_f32_e32 v108, v78
	v_mul_f32_e32 v78, v103, v105
	v_cvt_pk_bf16_f32 v78, v78, s0
	ds_write_b16 v195, v78 offset:1056
	v_add_f32_e32 v78, v104, v196
	v_mul_f32_e32 v103, 0x3fb8aa3b, v78
	v_exp_f32_e32 v103, v103
	v_min_f32_e64 v78, -v78, s88
	v_mul_f32_e32 v78, 0x3fb8aa3b, v78
	v_exp_f32_e32 v109, v78
	v_mul_f32_e32 v78, v102, v103
	v_lshlrev_b32_e32 v102, 16, v77
	v_and_b32_e32 v103, 0xffff0000, v77
	v_mul_f32_e32 v77, v108, v102
	v_cvt_pk_bf16_f32 v77, v77, s0
	ds_write_b16 v195, v77 offset:17952
	v_mul_f32_e32 v77, v109, v103
	v_cvt_pk_bf16_f32 v77, v77, s0
	v_cvt_pk_bf16_f32 v78, v78, s0
	ds_write_b16 v195, v77 offset:18480
	v_add_f32_e32 v77, v101, v196
	ds_write_b16 v195, v78 offset:1584
	v_mul_f32_e32 v78, 0x3fb8aa3b, v77
	v_exp_f32_e32 v78, v78
	v_min_f32_e64 v77, -v77, s88
	v_pk_mul_f32 v[104:105], v[0:1], v[108:109] op_sel_hi:[0,1]
	v_mul_f32_e32 v77, 0x3fb8aa3b, v77
	v_pk_mul_f32 v[102:103], v[104:105], v[102:103]
	v_exp_f32_e32 v104, v77
	v_mul_f32_e32 v77, v99, v78
	v_cvt_pk_bf16_f32 v77, v77, s0
	ds_write_b16 v195, v77 offset:2112
	v_add_f32_e32 v77, v100, v196
	v_mul_f32_e32 v78, 0x3fb8aa3b, v77
	v_exp_f32_e32 v78, v78
	v_min_f32_e64 v77, -v77, s88
	v_mul_f32_e32 v77, 0x3fb8aa3b, v77
	v_exp_f32_e32 v105, v77
	v_mul_f32_e32 v77, v98, v78
	v_cvt_pk_bf16_f32 v77, v77, s0
	ds_write_b16 v195, v77 offset:2640
	v_and_b32_e32 v77, 0xffff0000, v76
	v_lshlrev_b32_e32 v76, 16, v76
	v_mul_f32_e32 v78, v104, v76
	v_cvt_pk_bf16_f32 v78, v78, s0
	ds_write_b16 v195, v78 offset:19008
	v_mul_f32_e32 v78, v105, v77
	v_cvt_pk_bf16_f32 v78, v78, s0
	ds_write_b16 v195, v78 offset:19536
	v_add_f32_e32 v78, v97, v196
	v_mul_f32_e32 v97, 0x3fb8aa3b, v78
	v_exp_f32_e32 v97, v97
	v_min_f32_e64 v78, -v78, s88
	v_pk_mul_f32 v[98:99], v[0:1], v[104:105] op_sel_hi:[0,1]
	v_mul_f32_e32 v78, 0x3fb8aa3b, v78
	v_pk_mul_f32 v[76:77], v[98:99], v[76:77]
	v_exp_f32_e32 v98, v78
	v_mul_f32_e32 v78, v95, v97
	v_cvt_pk_bf16_f32 v78, v78, s0
	ds_write_b16 v195, v78 offset:3168
	v_add_f32_e32 v78, v96, v196
	v_mul_f32_e32 v95, 0x3fb8aa3b, v78
	v_exp_f32_e32 v95, v95
	v_min_f32_e64 v78, -v78, s88
	v_mul_f32_e32 v78, 0x3fb8aa3b, v78
	v_exp_f32_e32 v99, v78
	v_mul_f32_e32 v78, v94, v95
	v_lshlrev_b32_e32 v94, 16, v75
	v_and_b32_e32 v95, 0xffff0000, v75
	v_mul_f32_e32 v75, v98, v94
	v_cvt_pk_bf16_f32 v75, v75, s0
	ds_write_b16 v195, v75 offset:20064
	v_mul_f32_e32 v75, v99, v95
	v_cvt_pk_bf16_f32 v75, v75, s0
	v_cvt_pk_bf16_f32 v78, v78, s0
	ds_write_b16 v195, v75 offset:20592
; template <int K, bool HG>
; __device__ void chunk_item(const Ctx& cx, CParamsPtr pp, int l, int item, char* shm) {
;     ...
; #pragma unroll
;     for (int i = 0; i < TPS; ++i) {
;       const float bb = offs + bl[i];
;       const int t = seg * TPS + i;
;       const float eq = __expf(bb), ek = __expf(fminf(-bb, 85.0f)), ekp = etot * ek;
;       *(u16*)(QT + t * RS + kc * 2) = f2b(qvv[i] * eq);
;       *(u16*)(KT + t * RS + kc * 2) = f2b(kvv[i] * ek);
;       kpv[i] = kvv[i] * ekp;
;     }
; #pragma unroll
;     for (int i = 0; i < TPS / 2; ++i) kpw[i] = pack2(kpv[2 * i], kpv[2 * i + 1]);
; #pragma unroll
;     for (int i = 0; i < TPS / 8; ++i)
;       *(uint4*)(KP + kc * 80 + seg * TPS * 2 + i * 16) = make_uint4(kpw[i * 4], kpw[i * 4 + 1], kpw[i * 4 + 2], kpw[i * 4 + 3]);
;     if (seg == 0) EB[kc] = etot;
	v_add_f32_e32 v75, v93, v196
	ds_write_b16 v195, v78 offset:3696
	v_mul_f32_e32 v78, 0x3fb8aa3b, v75
	v_exp_f32_e32 v78, v78
	v_min_f32_e64 v75, -v75, s88
	v_pk_mul_f32 v[96:97], v[0:1], v[98:99] op_sel_hi:[0,1]
	v_mul_f32_e32 v75, 0x3fb8aa3b, v75
	v_pk_mul_f32 v[94:95], v[96:97], v[94:95]
	v_exp_f32_e32 v96, v75
	v_mul_f32_e32 v75, v91, v78
	v_cvt_pk_bf16_f32 v75, v75, s0
	ds_write_b16 v195, v75 offset:4224
	v_add_f32_e32 v75, v92, v196
	v_mul_f32_e32 v78, 0x3fb8aa3b, v75
	v_exp_f32_e32 v78, v78
	v_min_f32_e64 v75, -v75, s88
	v_mul_f32_e32 v75, 0x3fb8aa3b, v75
	v_exp_f32_e32 v97, v75
	v_mul_f32_e32 v75, v90, v78
	v_cvt_pk_bf16_f32 v75, v75, s0
	ds_write_b16 v195, v75 offset:4752
	v_and_b32_e32 v75, 0xffff0000, v74
	v_lshlrev_b32_e32 v74, 16, v74
	v_mul_f32_e32 v78, v96, v74
	v_pk_mul_f32 v[90:91], v[0:1], v[96:97] op_sel_hi:[0,1]
	v_cvt_pk_bf16_f32 v78, v78, s0
	v_pk_mul_f32 v[90:91], v[90:91], v[74:75]
	v_add_f32_e32 v74, v89, v196
	ds_write_b16 v195, v78 offset:21120
	v_mul_f32_e32 v78, v97, v75
	v_mul_f32_e32 v75, 0x3fb8aa3b, v74
	v_exp_f32_e32 v75, v75
	v_cvt_pk_bf16_f32 v78, v78, s0
	ds_write_b16 v195, v78 offset:21648
	v_min_f32_e64 v74, -v74, s88
	v_mul_f32_e32 v75, v87, v75
	v_cvt_pk_bf16_f32 v75, v75, s0
	ds_write_b16 v195, v75 offset:5280
	v_add_f32_e32 v75, v88, v196
	v_mul_f32_e32 v78, 0x3fb8aa3b, v75
	v_mul_f32_e32 v74, 0x3fb8aa3b, v74
	v_exp_f32_e32 v78, v78
	v_exp_f32_e32 v74, v74
	v_min_f32_e64 v75, -v75, s88
	v_mul_f32_e32 v75, 0x3fb8aa3b, v75
	v_exp_f32_e32 v75, v75
	v_mul_f32_e32 v78, v86, v78
	v_lshlrev_b32_e32 v86, 16, v73
	v_and_b32_e32 v87, 0xffff0000, v73
	v_mul_f32_e32 v73, v74, v86
	v_cvt_pk_bf16_f32 v73, v73, s0
	ds_write_b16 v195, v73 offset:22176
	v_mul_f32_e32 v73, v75, v87
	v_cvt_pk_bf16_f32 v73, v73, s0
	ds_write_b16 v195, v73 offset:22704
	v_add_f32_e32 v73, v85, v196
	v_pk_mul_f32 v[88:89], v[0:1], v[74:75] op_sel_hi:[0,1]
	v_mul_f32_e32 v74, 0x3fb8aa3b, v73
	v_exp_f32_e32 v75, v74
	v_min_f32_e64 v73, -v73, s88
	v_mul_f32_e32 v73, 0x3fb8aa3b, v73
	v_exp_f32_e32 v74, v73
	v_mul_f32_e32 v73, v83, v75
	v_cvt_pk_bf16_f32 v73, v73, s0
	ds_write_b16 v195, v73 offset:6336
	v_add_f32_e32 v73, v84, v196
	v_cvt_pk_bf16_f32 v78, v78, s0
	v_mul_f32_e32 v75, 0x3fb8aa3b, v73
	ds_write_b16 v195, v78 offset:5808
	v_exp_f32_e32 v78, v75
	v_min_f32_e64 v73, -v73, s88
	v_mul_f32_e32 v73, 0x3fb8aa3b, v73
	v_exp_f32_e32 v75, v73
	v_mul_f32_e32 v73, v82, v78
	v_cvt_pk_bf16_f32 v73, v73, s0
	ds_write_b16 v195, v73 offset:6864
	v_and_b32_e32 v73, 0xffff0000, v72
	v_lshlrev_b32_e32 v72, 16, v72
	v_pk_mul_f32 v[82:83], v[0:1], v[74:75] op_sel_hi:[0,1]
	v_mul_f32_e32 v78, v74, v72
	v_pk_mul_f32 v[82:83], v[82:83], v[72:73]
	v_add_f32_e32 v72, v81, v196
	v_mul_f32_e32 v74, v75, v73
	v_mul_f32_e32 v73, 0x3fb8aa3b, v72
	v_exp_f32_e32 v73, v73
	v_cvt_pk_bf16_f32 v74, v74, s0
	ds_write_b16 v195, v74 offset:23760
	v_min_f32_e64 v72, -v72, s88
	v_mul_f32_e32 v73, v79, v73
	v_cvt_pk_bf16_f32 v73, v73, s0
	ds_write_b16 v195, v73 offset:7392
	v_add_f32_e32 v73, v80, v196
	v_mul_f32_e32 v74, 0x3fb8aa3b, v73
	v_mul_f32_e32 v72, 0x3fb8aa3b, v72
	v_exp_f32_e32 v74, v74
	v_exp_f32_e32 v72, v72
	v_min_f32_e64 v73, -v73, s88
	v_mul_f32_e32 v73, 0x3fb8aa3b, v73
	v_exp_f32_e32 v73, v73
	v_mul_f32_e32 v2, v2, v74
	v_lshlrev_b32_e32 v74, 16, v1
	v_and_b32_e32 v75, 0xffff0000, v1
	v_mul_f32_e32 v1, v72, v74
	v_cvt_pk_bf16_f32 v78, v78, s0
	v_cvt_pk_bf16_f32 v1, v1, s0
	ds_write_b16 v195, v78 offset:23232
	ds_write_b16 v195, v1 offset:24288
	v_pk_mul_f32 v[78:79], v[0:1], v[72:73] op_sel_hi:[0,1]
	v_mul_f32_e32 v1, v73, v75
	v_cvt_pk_bf16_f32 v1, v1, s0
	v_cvt_pk_bf16_f32 v2, v2, s0
	ds_write_b16 v195, v1 offset:24816
	v_add_u32_e32 v1, s28, v158
	v_pk_mul_f32 v[86:87], v[88:89], v[86:87]
	ds_write_b16 v195, v2 offset:7920
	v_pk_mul_f32 v[80:81], v[78:79], v[74:75]
	v_cvt_pk_bf16_f32 v72, v106, v107
	v_cvt_pk_bf16_f32 v73, v102, v103
	v_cvt_pk_bf16_f32 v74, v76, v77
	v_cvt_pk_bf16_f32 v75, v94, v95
	v_add_u32_e32 v2, v1, v159
	v_cvt_pk_bf16_f32 v76, v90, v91
	v_cvt_pk_bf16_f32 v77, v86, v87
	v_cvt_pk_bf16_f32 v78, v82, v83
	v_cvt_pk_bf16_f32 v79, v80, v81
	ds_write_b128 v2, v[72:75] offset:33792
	ds_write_b128 v2, v[76:79] offset:33808
	s_and_saveexec_b64 s[18:19], vcc
	s_cbranch_execz .LBB0_201
	v_add_u32_e32 v1, v1, v161
	ds_write_b32 v1, v0 offset:64512
	s_branch .LBB0_201
